# candC + PEER step-A reduction: bit-2 stage via one v_add_f32_dpp row_half_mirror instead of two bank-masked DPP moves + add
# speedup vs baseline: 1.0131x; 1.0131x over previous
; __device__ __forceinline__ f32x2 fp8x2_lo(unsigned w) { return __builtin_amdgcn_cvt_pk_f32_fp8(w, false); }
; __device__ __forceinline__ f32x2 fp8x2_hi(unsigned w) { return __builtin_amdgcn_cvt_pk_f32_fp8(w, true); }
; #define PA_IDS(T) do { const unsigned* kp_ = KP + (size_t)(T) * 256; _Pragma("unroll") for (int qq = 0; qq < 4; ++qq) idv[qq] = *(const u32x4*)(kp_ + 4 * qq); } while (0)
; template <bool NT>
; __device__ __forceinline__ void peer_passA(const Args& a, const PeerWork w) {
;     ...
;     int t = peer_tok(w, q), t1 = peer_tok(w, min(q + qs, ql));
;     PA_IDS(t);
;     PA_GATHER(t, ur, hv);
;     PA_IDS(t1);
; #pragma unroll 1
;     for (;; q += qs) {
;         u32x4 urn[16]; f32x4 hn[4];
;         PA_GATHER(t1, urn, hn);
;         const int t2 = peer_tok(w, min(q + 2 * qs, ql));
;         PA_IDS(t2);
;         float part[16];
; #pragma unroll
;         for (int k = 0; k < 16; ++k) {
;             const unsigned ww[4] = {ur[k].x, ur[k].y, ur[k].z, ur[k].w};
;             f32x2 p2 = {0.f, 0.f};
; #pragma unroll
;             for (int wd = 0; wd < 4; ++wd) { p2 = __builtin_elementwise_fma(fp8x2_lo(ww[wd]), (f32x2){hv[wd][0], hv[wd][1]}, p2); p2 = __builtin_elementwise_fma(fp8x2_hi(ww[wd]), (f32x2){hv[wd][2], hv[wd][3]}, p2); }
;             part[k] = p2[0] + p2[1];
.LBB0_1321:
	s_waitcnt vmcnt(24)
	v_cvt_pk_f32_fp8_e32 v[184:185], v180
	v_cvt_pk_f32_fp8_sdwa v[186:187], v180 src0_sel:WORD_1
	v_cvt_pk_f32_fp8_e32 v[188:189], v181
	v_cvt_pk_f32_fp8_sdwa v[180:181], v181 src0_sel:WORD_1
	s_waitcnt vmcnt(5)
	v_pk_fma_f32 v[184:185], v[184:185], v[94:95], 0 op_sel_hi:[1,1,0]
	v_pk_fma_f32 v[184:185], v[186:187], v[96:97], v[184:185]
	v_cvt_pk_f32_fp8_sdwa v[186:187], v182 src0_sel:WORD_1
	v_pk_fma_f32 v[184:185], v[188:189], v[90:91], v[184:185]
	v_cvt_pk_f32_fp8_e32 v[188:189], v183
	v_pk_fma_f32 v[180:181], v[180:181], v[92:93], v[184:185]
	v_cvt_pk_f32_fp8_e32 v[184:185], v182
	v_cvt_pk_f32_fp8_sdwa v[182:183], v183 src0_sel:WORD_1
	v_pk_fma_f32 v[180:181], v[184:185], v[86:87], v[180:181]
	v_cvt_pk_f32_fp8_e32 v[184:185], v177
	v_pk_fma_f32 v[180:181], v[186:187], v[88:89], v[180:181]
	v_pk_fma_f32 v[180:181], v[188:189], v[82:83], v[180:181]
	v_pk_fma_f32 v[180:181], v[182:183], v[84:85], v[180:181]
	v_cvt_pk_f32_fp8_sdwa v[182:183], v176 src0_sel:WORD_1
	v_add_f32_e32 v186, v180, v181
	v_cvt_pk_f32_fp8_e32 v[180:181], v176
	v_cvt_pk_f32_fp8_sdwa v[176:177], v177 src0_sel:WORD_1
	v_pk_fma_f32 v[180:181], v[180:181], v[94:95], 0 op_sel_hi:[1,1,0]
	v_pk_fma_f32 v[180:181], v[182:183], v[96:97], v[180:181]
	v_cvt_pk_f32_fp8_sdwa v[182:183], v178 src0_sel:WORD_1
	v_pk_fma_f32 v[180:181], v[184:185], v[90:91], v[180:181]
	v_cvt_pk_f32_fp8_e32 v[184:185], v179
	v_pk_fma_f32 v[176:177], v[176:177], v[92:93], v[180:181]
	v_cvt_pk_f32_fp8_e32 v[180:181], v178
	v_cvt_pk_f32_fp8_sdwa v[178:179], v179 src0_sel:WORD_1
	v_pk_fma_f32 v[176:177], v[180:181], v[86:87], v[176:177]
	v_cvt_pk_f32_fp8_e32 v[180:181], v173
	v_pk_fma_f32 v[176:177], v[182:183], v[88:89], v[176:177]
	v_pk_fma_f32 v[176:177], v[184:185], v[82:83], v[176:177]
	v_pk_fma_f32 v[176:177], v[178:179], v[84:85], v[176:177]
	v_cvt_pk_f32_fp8_sdwa v[178:179], v172 src0_sel:WORD_1
	v_add_f32_e32 v182, v176, v177
	v_cvt_pk_f32_fp8_e32 v[176:177], v172
	v_cvt_pk_f32_fp8_sdwa v[172:173], v173 src0_sel:WORD_1
	v_pk_fma_f32 v[176:177], v[176:177], v[94:95], 0 op_sel_hi:[1,1,0]
	v_pk_fma_f32 v[176:177], v[178:179], v[96:97], v[176:177]
	v_cvt_pk_f32_fp8_sdwa v[178:179], v174 src0_sel:WORD_1
	v_pk_fma_f32 v[176:177], v[180:181], v[90:91], v[176:177]
	v_cvt_pk_f32_fp8_e32 v[180:181], v175
	v_pk_fma_f32 v[172:173], v[172:173], v[92:93], v[176:177]
	v_cvt_pk_f32_fp8_e32 v[176:177], v174
	v_cvt_pk_f32_fp8_sdwa v[174:175], v175 src0_sel:WORD_1
	v_pk_fma_f32 v[172:173], v[176:177], v[86:87], v[172:173]
	v_cvt_pk_f32_fp8_e32 v[176:177], v169
	v_pk_fma_f32 v[172:173], v[178:179], v[88:89], v[172:173]
	v_pk_fma_f32 v[172:173], v[180:181], v[82:83], v[172:173]
	v_pk_fma_f32 v[172:173], v[174:175], v[84:85], v[172:173]
	v_cvt_pk_f32_fp8_sdwa v[174:175], v168 src0_sel:WORD_1
	v_add_f32_e32 v178, v172, v173
	v_cvt_pk_f32_fp8_e32 v[172:173], v168
	v_cvt_pk_f32_fp8_sdwa v[168:169], v169 src0_sel:WORD_1
	v_pk_fma_f32 v[172:173], v[172:173], v[94:95], 0 op_sel_hi:[1,1,0]
	v_pk_fma_f32 v[172:173], v[174:175], v[96:97], v[172:173]
	v_cvt_pk_f32_fp8_sdwa v[174:175], v170 src0_sel:WORD_1
	v_pk_fma_f32 v[172:173], v[176:177], v[90:91], v[172:173]
	v_cvt_pk_f32_fp8_e32 v[176:177], v171
	v_pk_fma_f32 v[168:169], v[168:169], v[92:93], v[172:173]
	v_cvt_pk_f32_fp8_e32 v[172:173], v170
	v_cvt_pk_f32_fp8_sdwa v[170:171], v171 src0_sel:WORD_1
	s_waitcnt vmcnt(1)
	v_lshl_or_b32 v10, v30, 7, v1
	v_pk_fma_f32 v[168:169], v[172:173], v[86:87], v[168:169]
	v_cvt_pk_f32_fp8_e32 v[172:173], v165
	v_pk_fma_f32 v[168:169], v[174:175], v[88:89], v[168:169]
	v_lshl_or_b32 v11, v31, 7, v1
	v_pk_fma_f32 v[168:169], v[176:177], v[82:83], v[168:169]
	v_lshl_or_b32 v22, v32, 7, v1
	v_pk_fma_f32 v[168:169], v[170:171], v[84:85], v[168:169]
	v_cvt_pk_f32_fp8_sdwa v[170:171], v164 src0_sel:WORD_1
	v_add_f32_e32 v174, v168, v169
	v_cvt_pk_f32_fp8_e32 v[168:169], v164
	v_cvt_pk_f32_fp8_sdwa v[164:165], v165 src0_sel:WORD_1
	v_lshl_or_b32 v23, v33, 7, v1
	v_lshl_or_b32 v18, v18, 7, v1
	v_pk_fma_f32 v[168:169], v[168:169], v[94:95], 0 op_sel_hi:[1,1,0]
	v_lshl_or_b32 v19, v19, 7, v1
	v_pk_fma_f32 v[168:169], v[170:171], v[96:97], v[168:169]
	v_cvt_pk_f32_fp8_sdwa v[170:171], v166 src0_sel:WORD_1
	v_pk_fma_f32 v[168:169], v[172:173], v[90:91], v[168:169]
	v_cvt_pk_f32_fp8_e32 v[172:173], v167
	v_pk_fma_f32 v[164:165], v[164:165], v[92:93], v[168:169]
	v_cvt_pk_f32_fp8_e32 v[168:169], v166
	v_cvt_pk_f32_fp8_sdwa v[166:167], v167 src0_sel:WORD_1
	global_load_dwordx4 v[2:5], v10, s[10:11]
	global_load_dwordx4 v[6:9], v11, s[10:11]
	v_pk_fma_f32 v[164:165], v[168:169], v[86:87], v[164:165]
	v_cvt_pk_f32_fp8_e32 v[168:169], v161
	v_pk_fma_f32 v[164:165], v[170:171], v[88:89], v[164:165]
	global_load_dwordx4 v[10:13], v22, s[10:11]
	global_load_dwordx4 v[14:17], v23, s[10:11]
	v_pk_fma_f32 v[164:165], v[172:173], v[82:83], v[164:165]
	global_load_dwordx4 v[22:25], v18, s[10:11]
	global_load_dwordx4 v[26:29], v19, s[10:11]
	v_pk_fma_f32 v[164:165], v[166:167], v[84:85], v[164:165]
	v_cvt_pk_f32_fp8_sdwa v[166:167], v160 src0_sel:WORD_1
	v_add_f32_e32 v170, v164, v165
	v_cvt_pk_f32_fp8_e32 v[164:165], v160
	v_cvt_pk_f32_fp8_sdwa v[160:161], v161 src0_sel:WORD_1
	v_lshl_or_b32 v18, v20, 7, v1
	v_lshl_or_b32 v19, v21, 7, v1
	v_pk_fma_f32 v[164:165], v[164:165], v[94:95], 0 op_sel_hi:[1,1,0]
	global_load_dwordx4 v[34:37], v18, s[10:11]
	global_load_dwordx4 v[38:41], v19, s[10:11]
	v_pk_fma_f32 v[164:165], v[166:167], v[96:97], v[164:165]
	v_cvt_pk_f32_fp8_sdwa v[166:167], v162 src0_sel:WORD_1
	v_pk_fma_f32 v[164:165], v[168:169], v[90:91], v[164:165]
	v_cvt_pk_f32_fp8_e32 v[168:169], v163
; __device__ __forceinline__ f32x2 fp8x2_lo(unsigned w) { return __builtin_amdgcn_cvt_pk_f32_fp8(w, false); }
; __device__ __forceinline__ f32x2 fp8x2_hi(unsigned w) { return __builtin_amdgcn_cvt_pk_f32_fp8(w, true); }
; #define PA_IDS(T) do { const unsigned* kp_ = KP + (size_t)(T) * 256; _Pragma("unroll") for (int qq = 0; qq < 4; ++qq) idv[qq] = *(const u32x4*)(kp_ + 4 * qq); } while (0)
; template <bool NT>
; __device__ __forceinline__ void peer_passA(const Args& a, const PeerWork w) {
;     ...
;     int t = peer_tok(w, q), t1 = peer_tok(w, min(q + qs, ql));
;     PA_IDS(t);
;     PA_GATHER(t, ur, hv);
;     PA_IDS(t1);
; #pragma unroll 1
;     for (;; q += qs) {
;         u32x4 urn[16]; f32x4 hn[4];
;         PA_GATHER(t1, urn, hn);
;         const int t2 = peer_tok(w, min(q + 2 * qs, ql));
;         PA_IDS(t2);
;         float part[16];
; #pragma unroll
;         for (int k = 0; k < 16; ++k) {
;             const unsigned ww[4] = {ur[k].x, ur[k].y, ur[k].z, ur[k].w};
;             f32x2 p2 = {0.f, 0.f};
; #pragma unroll
;             for (int wd = 0; wd < 4; ++wd) { p2 = __builtin_elementwise_fma(fp8x2_lo(ww[wd]), (f32x2){hv[wd][0], hv[wd][1]}, p2); p2 = __builtin_elementwise_fma(fp8x2_hi(ww[wd]), (f32x2){hv[wd][2], hv[wd][3]}, p2); }
;             part[k] = p2[0] + p2[1];
	v_pk_fma_f32 v[160:161], v[160:161], v[92:93], v[164:165]
	v_cvt_pk_f32_fp8_e32 v[164:165], v162
	v_cvt_pk_f32_fp8_sdwa v[162:163], v163 src0_sel:WORD_1
	v_lshl_or_b32 v18, v62, 7, v1
	v_lshl_or_b32 v19, v63, 7, v1
	v_pk_fma_f32 v[160:161], v[164:165], v[86:87], v[160:161]
	v_cvt_pk_f32_fp8_e32 v[164:165], v151
	v_pk_fma_f32 v[160:161], v[166:167], v[88:89], v[160:161]
	global_load_dwordx4 v[42:45], v18, s[10:11]
	global_load_dwordx4 v[46:49], v19, s[10:11]
	v_pk_fma_f32 v[160:161], v[168:169], v[82:83], v[160:161]
	v_lshl_or_b32 v18, v64, 7, v1
	v_pk_fma_f32 v[160:161], v[162:163], v[84:85], v[160:161]
	v_cvt_pk_f32_fp8_sdwa v[162:163], v150 src0_sel:WORD_1
	v_add_f32_e32 v166, v160, v161
	v_cvt_pk_f32_fp8_e32 v[160:161], v150
	v_cvt_pk_f32_fp8_sdwa v[150:151], v151 src0_sel:WORD_1
	v_lshl_or_b32 v19, v65, 7, v1
	s_mov_b32 s18, s16
	v_pk_fma_f32 v[160:161], v[160:161], v[94:95], 0 op_sel_hi:[1,1,0]
	s_mov_b32 s16, s14
	v_pk_fma_f32 v[160:161], v[162:163], v[96:97], v[160:161]
	v_cvt_pk_f32_fp8_sdwa v[162:163], v152 src0_sel:WORD_1
	v_pk_fma_f32 v[160:161], v[164:165], v[90:91], v[160:161]
	v_cvt_pk_f32_fp8_e32 v[164:165], v153
	v_pk_fma_f32 v[150:151], v[150:151], v[92:93], v[160:161]
	v_cvt_pk_f32_fp8_e32 v[160:161], v152
	v_cvt_pk_f32_fp8_sdwa v[152:153], v153 src0_sel:WORD_1
	global_load_dwordx4 v[54:57], v18, s[10:11]
	global_load_dwordx4 v[58:61], v19, s[10:11]
	v_pk_fma_f32 v[150:151], v[160:161], v[86:87], v[150:151]
	v_cvt_pk_f32_fp8_e32 v[160:161], v147
	v_pk_fma_f32 v[150:151], v[162:163], v[88:89], v[150:151]
	v_lshl_or_b32 v18, v50, 7, v1
	v_pk_fma_f32 v[150:151], v[164:165], v[82:83], v[150:151]
	v_lshl_or_b32 v19, v51, 7, v1
	v_pk_fma_f32 v[150:151], v[152:153], v[84:85], v[150:151]
	v_cvt_pk_f32_fp8_sdwa v[152:153], v146 src0_sel:WORD_1
	v_add_f32_e32 v162, v150, v151
	v_cvt_pk_f32_fp8_e32 v[150:151], v146
	v_cvt_pk_f32_fp8_sdwa v[146:147], v147 src0_sel:WORD_1
	s_ashr_i32 s17, s14, 31
	v_pk_fma_f32 v[150:151], v[150:151], v[94:95], 0 op_sel_hi:[1,1,0]
	v_pk_fma_f32 v[150:151], v[152:153], v[96:97], v[150:151]
	v_cvt_pk_f32_fp8_sdwa v[152:153], v148 src0_sel:WORD_1
	v_pk_fma_f32 v[150:151], v[160:161], v[90:91], v[150:151]
	v_cvt_pk_f32_fp8_e32 v[160:161], v149
	v_pk_fma_f32 v[146:147], v[146:147], v[92:93], v[150:151]
	v_cvt_pk_f32_fp8_e32 v[150:151], v148
	v_cvt_pk_f32_fp8_sdwa v[148:149], v149 src0_sel:WORD_1
	global_load_dwordx4 v[66:69], v18, s[10:11]
	global_load_dwordx4 v[70:73], v19, s[10:11]
	v_pk_fma_f32 v[146:147], v[150:151], v[86:87], v[146:147]
	v_cvt_pk_f32_fp8_e32 v[150:151], v143
	v_pk_fma_f32 v[146:147], v[152:153], v[88:89], v[146:147]
	v_lshl_or_b32 v18, v52, 7, v1
	v_pk_fma_f32 v[146:147], v[160:161], v[82:83], v[146:147]
	v_lshl_or_b32 v19, v53, 7, v1
	v_pk_fma_f32 v[146:147], v[148:149], v[84:85], v[146:147]
	v_cvt_pk_f32_fp8_sdwa v[148:149], v142 src0_sel:WORD_1
	v_add_f32_e32 v152, v146, v147
	v_cvt_pk_f32_fp8_e32 v[146:147], v142
	v_cvt_pk_f32_fp8_sdwa v[142:143], v143 src0_sel:WORD_1
	s_lshl_b64 s[14:15], s[16:17], 12
	s_add_i32 s17, s12, s13
	v_pk_fma_f32 v[146:147], v[146:147], v[94:95], 0 op_sel_hi:[1,1,0]
	v_pk_fma_f32 v[146:147], v[148:149], v[96:97], v[146:147]
	v_cvt_pk_f32_fp8_sdwa v[148:149], v144 src0_sel:WORD_1
	v_pk_fma_f32 v[146:147], v[150:151], v[90:91], v[146:147]
	v_cvt_pk_f32_fp8_e32 v[150:151], v145
	v_pk_fma_f32 v[142:143], v[142:143], v[92:93], v[146:147]
	v_cvt_pk_f32_fp8_e32 v[146:147], v144
	v_cvt_pk_f32_fp8_sdwa v[144:145], v145 src0_sel:WORD_1
	global_load_dwordx4 v[74:77], v18, s[10:11]
	global_load_dwordx4 v[78:81], v19, s[10:11]
	v_pk_fma_f32 v[142:143], v[146:147], v[86:87], v[142:143]
	v_cvt_pk_f32_fp8_e32 v[146:147], v139
	v_pk_fma_f32 v[142:143], v[148:149], v[88:89], v[142:143]
	v_lshl_add_u64 v[18:19], v[156:157], 0, s[14:15]
	v_pk_fma_f32 v[142:143], v[150:151], v[82:83], v[142:143]
	s_min_i32 s14, s17, 0x3fff
	v_pk_fma_f32 v[142:143], v[144:145], v[84:85], v[142:143]
	v_cvt_pk_f32_fp8_sdwa v[144:145], v138 src0_sel:WORD_1
	v_add_f32_e32 v148, v142, v143
	v_cvt_pk_f32_fp8_e32 v[142:143], v138
	v_cvt_pk_f32_fp8_sdwa v[138:139], v139 src0_sel:WORD_1
	s_ashr_i32 s15, s14, 31
	s_lshl_b64 s[28:29], s[14:15], 10
	v_pk_fma_f32 v[142:143], v[142:143], v[94:95], 0 op_sel_hi:[1,1,0]
	v_lshl_add_u64 v[30:31], v[154:155], 0, s[28:29]
	v_pk_fma_f32 v[142:143], v[144:145], v[96:97], v[142:143]
	v_cvt_pk_f32_fp8_sdwa v[144:145], v140 src0_sel:WORD_1
	v_pk_fma_f32 v[142:143], v[146:147], v[90:91], v[142:143]
	v_cvt_pk_f32_fp8_e32 v[146:147], v141
	v_pk_fma_f32 v[138:139], v[138:139], v[92:93], v[142:143]
	v_cvt_pk_f32_fp8_e32 v[142:143], v140
	v_cvt_pk_f32_fp8_sdwa v[140:141], v141 src0_sel:WORD_1
	global_load_dwordx4 v[110:113], v[18:19], off offset:48
	global_load_dwordx4 v[106:109], v[18:19], off offset:32
	global_load_dwordx4 v[102:105], v[18:19], off offset:16
	global_load_dwordx4 v[98:101], v[18:19], off
	global_load_dwordx4 v[50:53], v[30:31], off offset:48
	global_load_dwordx4 v[62:65], v[30:31], off offset:32
	s_nop 0
	global_load_dwordx4 v[18:21], v[30:31], off offset:16
	s_nop 0
	global_load_dwordx4 v[30:33], v[30:31], off
	v_pk_fma_f32 v[138:139], v[142:143], v[86:87], v[138:139]
	v_cvt_pk_f32_fp8_e32 v[142:143], v135
	v_pk_fma_f32 v[138:139], v[144:145], v[88:89], v[138:139]
	s_ashr_i32 s19, s18, 31
	v_pk_fma_f32 v[138:139], v[146:147], v[82:83], v[138:139]
	s_lshl_b64 s[18:19], s[18:19], 11
	v_pk_fma_f32 v[138:139], v[140:141], v[84:85], v[138:139]
	v_cvt_pk_f32_fp8_sdwa v[140:141], v134 src0_sel:WORD_1
	v_add_f32_e32 v144, v138, v139
	v_cvt_pk_f32_fp8_e32 v[138:139], v134
	v_cvt_pk_f32_fp8_sdwa v[134:135], v135 src0_sel:WORD_1
	s_add_i32 s12, s22, s12
; __device__ __forceinline__ f32x2 fp8x2_lo(unsigned w) { return __builtin_amdgcn_cvt_pk_f32_fp8(w, false); }
; __device__ __forceinline__ f32x2 fp8x2_hi(unsigned w) { return __builtin_amdgcn_cvt_pk_f32_fp8(w, true); }
; __device__ __forceinline__ float xor4_f(float x) { float r = dpp_bank_f<0x104, 0x5>(0.f, x); return dpp_bank_f<0x114, 0xa>(r, x); }
; template <bool NT>
; __device__ __forceinline__ void peer_passA(const Args& a, const PeerWork w) {
;     ...
;         for (int k = 0; k < 16; ++k) {
;             const unsigned ww[4] = {ur[k].x, ur[k].y, ur[k].z, ur[k].w};
;             f32x2 p2 = {0.f, 0.f};
; #pragma unroll
;             for (int wd = 0; wd < 4; ++wd) { p2 = __builtin_elementwise_fma(fp8x2_lo(ww[wd]), (f32x2){hv[wd][0], hv[wd][1]}, p2); p2 = __builtin_elementwise_fma(fp8x2_hi(ww[wd]), (f32x2){hv[wd][2], hv[wd][3]}, p2); }
;             part[k] = p2[0] + p2[1];
;         }
;         float w8[8], w4[4], w2[2];
;         { const bool up = (lane & 4) != 0;
; #pragma unroll
;           for (int m = 0; m < 8; ++m) { const float keep = up ? part[m + 8] : part[m], send = up ? part[m] : part[m + 8]; w8[m] = keep + xor4_f(send); } }
	s_cmpk_gt_i32 s12, 0x3fff
	v_pk_fma_f32 v[138:139], v[138:139], v[94:95], 0 op_sel_hi:[1,1,0]
	v_readfirstlane_b32 s12, v0
	v_pk_fma_f32 v[138:139], v[140:141], v[96:97], v[138:139]
	v_cvt_pk_f32_fp8_sdwa v[140:141], v136 src0_sel:WORD_1
	v_pk_fma_f32 v[138:139], v[142:143], v[90:91], v[138:139]
	v_cvt_pk_f32_fp8_e32 v[142:143], v137
	v_pk_fma_f32 v[134:135], v[134:135], v[92:93], v[138:139]
	v_cvt_pk_f32_fp8_e32 v[138:139], v136
	v_cvt_pk_f32_fp8_sdwa v[136:137], v137 src0_sel:WORD_1
	v_pk_fma_f32 v[134:135], v[138:139], v[86:87], v[134:135]
	s_nop 0
	v_pk_fma_f32 v[134:135], v[140:141], v[88:89], v[134:135]
	v_cvt_pk_f32_fp8_e32 v[138:139], v131
	v_pk_fma_f32 v[134:135], v[142:143], v[82:83], v[134:135]
	s_nop 0
	v_pk_fma_f32 v[134:135], v[136:137], v[84:85], v[134:135]
	v_cvt_pk_f32_fp8_sdwa v[136:137], v130 src0_sel:WORD_1
	v_add_f32_e32 v140, v134, v135
	v_cvt_pk_f32_fp8_e32 v[134:135], v130
	v_cvt_pk_f32_fp8_sdwa v[130:131], v131 src0_sel:WORD_1
	v_pk_fma_f32 v[134:135], v[134:135], v[94:95], 0 op_sel_hi:[1,1,0]
	s_nop 0
	v_pk_fma_f32 v[134:135], v[136:137], v[96:97], v[134:135]
	v_cvt_pk_f32_fp8_sdwa v[136:137], v132 src0_sel:WORD_1
	v_pk_fma_f32 v[134:135], v[138:139], v[90:91], v[134:135]
	v_cvt_pk_f32_fp8_e32 v[138:139], v133
	v_pk_fma_f32 v[130:131], v[130:131], v[92:93], v[134:135]
	v_cvt_pk_f32_fp8_e32 v[134:135], v132
	v_cvt_pk_f32_fp8_sdwa v[132:133], v133 src0_sel:WORD_1
	v_pk_fma_f32 v[130:131], v[134:135], v[86:87], v[130:131]
	s_nop 0
	v_pk_fma_f32 v[130:131], v[136:137], v[88:89], v[130:131]
	v_cvt_pk_f32_fp8_e32 v[134:135], v127
	v_pk_fma_f32 v[130:131], v[138:139], v[82:83], v[130:131]
	s_nop 0
	v_pk_fma_f32 v[130:131], v[132:133], v[84:85], v[130:131]
	v_cvt_pk_f32_fp8_sdwa v[132:133], v126 src0_sel:WORD_1
	v_add_f32_e32 v136, v130, v131
	v_cvt_pk_f32_fp8_e32 v[130:131], v126
	v_cvt_pk_f32_fp8_sdwa v[126:127], v127 src0_sel:WORD_1
	v_pk_fma_f32 v[130:131], v[130:131], v[94:95], 0 op_sel_hi:[1,1,0]
	s_nop 0
	v_pk_fma_f32 v[130:131], v[132:133], v[96:97], v[130:131]
	v_cvt_pk_f32_fp8_sdwa v[132:133], v128 src0_sel:WORD_1
	v_pk_fma_f32 v[130:131], v[134:135], v[90:91], v[130:131]
	v_cvt_pk_f32_fp8_e32 v[134:135], v129
	v_pk_fma_f32 v[126:127], v[126:127], v[92:93], v[130:131]
	v_cvt_pk_f32_fp8_e32 v[130:131], v128
	v_cvt_pk_f32_fp8_sdwa v[128:129], v129 src0_sel:WORD_1
	v_pk_fma_f32 v[126:127], v[130:131], v[86:87], v[126:127]
	s_nop 0
	v_pk_fma_f32 v[126:127], v[132:133], v[88:89], v[126:127]
	v_cvt_pk_f32_fp8_e32 v[130:131], v123
	v_pk_fma_f32 v[126:127], v[134:135], v[82:83], v[126:127]
	s_nop 0
	v_pk_fma_f32 v[126:127], v[128:129], v[84:85], v[126:127]
	v_cvt_pk_f32_fp8_sdwa v[128:129], v122 src0_sel:WORD_1
	v_add_f32_e32 v132, v126, v127
	v_cvt_pk_f32_fp8_e32 v[126:127], v122
	v_cvt_pk_f32_fp8_sdwa v[122:123], v123 src0_sel:WORD_1
	v_pk_fma_f32 v[126:127], v[126:127], v[94:95], 0 op_sel_hi:[1,1,0]
	s_nop 0
	v_pk_fma_f32 v[126:127], v[128:129], v[96:97], v[126:127]
	v_cvt_pk_f32_fp8_sdwa v[128:129], v124 src0_sel:WORD_1
	v_pk_fma_f32 v[126:127], v[130:131], v[90:91], v[126:127]
	v_cvt_pk_f32_fp8_e32 v[130:131], v125
	v_pk_fma_f32 v[122:123], v[122:123], v[92:93], v[126:127]
	v_cvt_pk_f32_fp8_e32 v[126:127], v124
	v_cvt_pk_f32_fp8_sdwa v[124:125], v125 src0_sel:WORD_1
	v_pk_fma_f32 v[122:123], v[126:127], v[86:87], v[122:123]
	s_nop 0
	v_pk_fma_f32 v[122:123], v[128:129], v[88:89], v[122:123]
	v_cvt_pk_f32_fp8_e32 v[126:127], v119
	v_pk_fma_f32 v[122:123], v[130:131], v[82:83], v[122:123]
	s_nop 0
	v_pk_fma_f32 v[122:123], v[124:125], v[84:85], v[122:123]
	v_cvt_pk_f32_fp8_sdwa v[124:125], v118 src0_sel:WORD_1
	v_add_f32_e32 v128, v122, v123
	v_cvt_pk_f32_fp8_e32 v[122:123], v118
	v_cvt_pk_f32_fp8_sdwa v[118:119], v119 src0_sel:WORD_1
	v_pk_fma_f32 v[122:123], v[122:123], v[94:95], 0 op_sel_hi:[1,1,0]
	s_nop 0
	v_pk_fma_f32 v[122:123], v[124:125], v[96:97], v[122:123]
	v_cvt_pk_f32_fp8_sdwa v[124:125], v120 src0_sel:WORD_1
	v_pk_fma_f32 v[122:123], v[126:127], v[90:91], v[122:123]
	v_cvt_pk_f32_fp8_e32 v[126:127], v121
	v_pk_fma_f32 v[118:119], v[118:119], v[92:93], v[122:123]
	v_cvt_pk_f32_fp8_e32 v[122:123], v120
	v_cvt_pk_f32_fp8_sdwa v[120:121], v121 src0_sel:WORD_1
	v_pk_fma_f32 v[118:119], v[122:123], v[86:87], v[118:119]
	s_nop 0
	v_pk_fma_f32 v[118:119], v[124:125], v[88:89], v[118:119]
	v_cvt_pk_f32_fp8_e32 v[122:123], v115
	v_pk_fma_f32 v[118:119], v[126:127], v[82:83], v[118:119]
	s_nop 0
	v_pk_fma_f32 v[118:119], v[120:121], v[84:85], v[118:119]
	v_cvt_pk_f32_fp8_sdwa v[120:121], v114 src0_sel:WORD_1
	v_add_f32_e32 v124, v118, v119
	v_cvt_pk_f32_fp8_e32 v[118:119], v114
	v_cvt_pk_f32_fp8_sdwa v[114:115], v115 src0_sel:WORD_1
	v_pk_fma_f32 v[94:95], v[118:119], v[94:95], 0 op_sel_hi:[1,1,0]
	s_nop 0
	v_pk_fma_f32 v[94:95], v[120:121], v[96:97], v[94:95]
	v_cvt_pk_f32_fp8_e32 v[96:97], v117
	v_pk_fma_f32 v[90:91], v[122:123], v[90:91], v[94:95]
	v_cvt_pk_f32_fp8_sdwa v[94:95], v116 src0_sel:WORD_1
	v_pk_fma_f32 v[90:91], v[114:115], v[92:93], v[90:91]
	v_cvt_pk_f32_fp8_e32 v[92:93], v116
	v_cvt_pk_f32_fp8_sdwa v[114:115], v117 src0_sel:WORD_1
	v_pk_fma_f32 v[86:87], v[92:93], v[86:87], v[90:91]
	s_nop 0
	v_pk_fma_f32 v[86:87], v[94:95], v[88:89], v[86:87]
	v_pk_fma_f32 v[82:83], v[96:97], v[82:83], v[86:87]
	v_pk_fma_f32 v[82:83], v[114:115], v[84:85], v[82:83]
	v_cndmask_b32_e64 v84, v186, v148, s[0:1]
	v_add_f32_e32 v82, v82, v83
	v_cndmask_b32_e64 v83, v148, v186, s[0:1]
	s_nop 0
	v_add_f32_dpp v83, v84, v83 row_half_mirror row_mask:0xf bank_mask:0xf bound_ctrl:1
	v_cndmask_b32_e64 v85, v182, v144, s[0:1]
	v_cndmask_b32_e64 v84, v144, v182, s[0:1]
	s_nop 0
; __device__ __forceinline__ unsigned cvt_pk_bf16(float lo, float hi) { unsigned r; asm volatile("v_cvt_pk_bf16_f32 %0, %1, %2" : "=v"(r) : "v"(lo), "v"(hi)); return r; }
; template <int CTRL> __device__ __forceinline__ float dpp_f(float x) { return __uint_as_float((unsigned)__builtin_amdgcn_update_dpp(0, (int)__float_as_uint(x), CTRL, 0xf, 0xf, false)); }
; __device__ __forceinline__ f32x2 fp8x2_lo(unsigned w) { return __builtin_amdgcn_cvt_pk_f32_fp8(w, false); }
; __device__ __forceinline__ f32x2 fp8x2_hi(unsigned w) { return __builtin_amdgcn_cvt_pk_f32_fp8(w, true); }
; __device__ __forceinline__ float xor4_f(float x) { float r = dpp_bank_f<0x104, 0x5>(0.f, x); return dpp_bank_f<0x114, 0xa>(r, x); }
; template <bool NT>
; __device__ __forceinline__ void peer_passA(const Args& a, const PeerWork w) {
;     ...
;         for (int k = 0; k < 16; ++k) {
;             const unsigned ww[4] = {ur[k].x, ur[k].y, ur[k].z, ur[k].w};
;             f32x2 p2 = {0.f, 0.f};
; #pragma unroll
;             for (int wd = 0; wd < 4; ++wd) { p2 = __builtin_elementwise_fma(fp8x2_lo(ww[wd]), (f32x2){hv[wd][0], hv[wd][1]}, p2); p2 = __builtin_elementwise_fma(fp8x2_hi(ww[wd]), (f32x2){hv[wd][2], hv[wd][3]}, p2); }
;             part[k] = p2[0] + p2[1];
;         }
;         float w8[8], w4[4], w2[2];
;         { const bool up = (lane & 4) != 0;
; #pragma unroll
;           for (int m = 0; m < 8; ++m) { const float keep = up ? part[m + 8] : part[m], send = up ? part[m] : part[m + 8]; w8[m] = keep + xor4_f(send); } }
;         { const bool up = (lane & 2) != 0;
; #pragma unroll
;           for (int m = 0; m < 4; ++m) { const float keep = up ? w8[m + 4] : w8[m], send = up ? w8[m] : w8[m + 4]; w4[m] = keep + dpp_f<0x4E>(send); } }
;         { const bool up = (lane & 1) != 0;
; #pragma unroll
;           for (int m = 0; m < 2; ++m) { const float keep = up ? w4[m + 2] : w4[m], send = up ? w4[m] : w4[m + 2]; w2[m] = keep + dpp_f<0xB1>(send); } }
;         PD[(size_t)t * 512] = cvt_pk_bf16(w2[0], w2[1]);
;         if (q + qs > ql) break;
; #pragma unroll
;         for (int k = 0; k < 16; ++k) ur[k] = urn[k];
; #pragma unroll
;         for (int qq = 0; qq < 4; ++qq) hv[qq] = hn[qq];
;         t = t1; t1 = t2;
	v_add_f32_dpp v84, v85, v84 row_half_mirror row_mask:0xf bank_mask:0xf bound_ctrl:1
	v_cndmask_b32_e64 v86, v178, v140, s[0:1]
	v_cndmask_b32_e64 v85, v140, v178, s[0:1]
	s_nop 0
	s_nop 0
	v_add_f32_dpp v85, v86, v85 row_half_mirror row_mask:0xf bank_mask:0xf bound_ctrl:1
	v_cndmask_b32_e64 v87, v174, v136, s[0:1]
	v_cndmask_b32_e64 v86, v136, v174, s[0:1]
	s_nop 0
	s_nop 0
	v_add_f32_dpp v86, v87, v86 row_half_mirror row_mask:0xf bank_mask:0xf bound_ctrl:1
	v_cndmask_b32_e64 v88, v170, v132, s[0:1]
	v_cndmask_b32_e64 v87, v132, v170, s[0:1]
	s_nop 0
	s_nop 0
	v_add_f32_dpp v87, v88, v87 row_half_mirror row_mask:0xf bank_mask:0xf bound_ctrl:1
	v_cndmask_b32_e64 v89, v166, v128, s[0:1]
	v_cndmask_b32_e64 v88, v128, v166, s[0:1]
	s_nop 0
	s_nop 0
	v_add_f32_dpp v88, v89, v88 row_half_mirror row_mask:0xf bank_mask:0xf bound_ctrl:1
	v_cndmask_b32_e64 v90, v162, v124, s[0:1]
	v_cndmask_b32_e64 v89, v124, v162, s[0:1]
	s_nop 0
	s_nop 0
	v_add_f32_dpp v89, v90, v89 row_half_mirror row_mask:0xf bank_mask:0xf bound_ctrl:1
	v_cndmask_b32_e64 v90, v82, v152, s[0:1]
	v_cndmask_b32_e64 v82, v152, v82, s[0:1]
	v_mov_b32_e32 v91, 0
	s_nop 1
	s_nop 0
	v_add_f32_dpp v82, v82, v90 row_half_mirror row_mask:0xf bank_mask:0xf bound_ctrl:1
	v_cndmask_b32_e64 v90, v87, v83, s[4:5]
	v_cndmask_b32_e64 v83, v83, v87, s[4:5]
	v_cndmask_b32_e64 v87, v88, v84, s[4:5]
	v_cndmask_b32_e64 v84, v84, v88, s[4:5]
	v_add_f32_dpp v83, v83, v90 quad_perm:[2,3,0,1] row_mask:0xf bank_mask:0xf bound_ctrl:1
	s_nop 0
	v_add_f32_dpp v84, v84, v87 quad_perm:[2,3,0,1] row_mask:0xf bank_mask:0xf bound_ctrl:1
	v_cndmask_b32_e64 v87, v89, v85, s[4:5]
	v_cndmask_b32_e64 v85, v85, v89, s[4:5]
	s_nop 1
	v_add_f32_dpp v85, v85, v87 quad_perm:[2,3,0,1] row_mask:0xf bank_mask:0xf bound_ctrl:1
	v_cndmask_b32_e64 v87, v82, v86, s[4:5]
	v_cndmask_b32_e64 v82, v86, v82, s[4:5]
	v_cndmask_b32_e64 v86, v85, v83, s[6:7]
	v_cndmask_b32_e64 v83, v83, v85, s[6:7]
	v_add_f32_dpp v82, v82, v87 quad_perm:[2,3,0,1] row_mask:0xf bank_mask:0xf bound_ctrl:1
	v_cndmask_b32_e64 v85, v82, v84, s[6:7]
	v_cndmask_b32_e64 v82, v84, v82, s[6:7]
	v_add_f32_dpp v83, v83, v86 quad_perm:[1,0,3,2] row_mask:0xf bank_mask:0xf bound_ctrl:1
	s_nop 0
	v_add_f32_dpp v82, v82, v85 quad_perm:[1,0,3,2] row_mask:0xf bank_mask:0xf bound_ctrl:1
	v_cvt_pk_bf16_f32 v84, v83, v82
	v_lshl_add_u64 v[82:83], v[158:159], 0, s[18:19]
	s_mov_b64 s[18:19], -1
	global_store_dword v[82:83], v84, off
	s_cbranch_scc1 .LBB0_1323
	s_sub_i32 s12, s17, s22
	s_mov_b64 s[18:19], 0
	s_waitcnt vmcnt(24)
	v_cvt_pk_f32_fp8_e32 v[184:185], v2
	v_cvt_pk_f32_fp8_sdwa v[186:187], v2 src0_sel:WORD_1
	v_cvt_pk_f32_fp8_e32 v[188:189], v3
	v_cvt_pk_f32_fp8_sdwa v[2:3], v3 src0_sel:WORD_1
	s_waitcnt vmcnt(5)
	v_pk_fma_f32 v[184:185], v[184:185], v[98:99], 0 op_sel_hi:[1,1,0]
	v_pk_fma_f32 v[184:185], v[186:187], v[100:101], v[184:185]
	v_cvt_pk_f32_fp8_sdwa v[186:187], v4 src0_sel:WORD_1
	v_pk_fma_f32 v[184:185], v[188:189], v[102:103], v[184:185]
	v_cvt_pk_f32_fp8_e32 v[188:189], v5
	v_pk_fma_f32 v[2:3], v[2:3], v[104:105], v[184:185]
	v_cvt_pk_f32_fp8_e32 v[184:185], v4
	v_cvt_pk_f32_fp8_sdwa v[4:5], v5 src0_sel:WORD_1
	v_pk_fma_f32 v[2:3], v[184:185], v[106:107], v[2:3]
	v_cvt_pk_f32_fp8_e32 v[184:185], v7
	v_pk_fma_f32 v[2:3], v[186:187], v[108:109], v[2:3]
	v_pk_fma_f32 v[2:3], v[188:189], v[110:111], v[2:3]
	v_pk_fma_f32 v[2:3], v[4:5], v[112:113], v[2:3]
	v_cvt_pk_f32_fp8_sdwa v[4:5], v6 src0_sel:WORD_1
	v_add_f32_e32 v186, v2, v3
	v_cvt_pk_f32_fp8_e32 v[2:3], v6
	v_cvt_pk_f32_fp8_sdwa v[6:7], v7 src0_sel:WORD_1
	v_pk_fma_f32 v[2:3], v[2:3], v[98:99], 0 op_sel_hi:[1,1,0]
	v_pk_fma_f32 v[2:3], v[4:5], v[100:101], v[2:3]
	v_cvt_pk_f32_fp8_sdwa v[4:5], v8 src0_sel:WORD_1
	v_pk_fma_f32 v[2:3], v[184:185], v[102:103], v[2:3]
	v_cvt_pk_f32_fp8_e32 v[184:185], v9
	v_pk_fma_f32 v[6:7], v[6:7], v[104:105], v[2:3]
	v_cvt_pk_f32_fp8_e32 v[2:3], v8
	v_cvt_pk_f32_fp8_sdwa v[8:9], v9 src0_sel:WORD_1
	v_pk_fma_f32 v[6:7], v[2:3], v[106:107], v[6:7]
	v_cvt_pk_f32_fp8_e32 v[2:3], v11
	v_pk_fma_f32 v[6:7], v[4:5], v[108:109], v[6:7]
	v_pk_fma_f32 v[6:7], v[184:185], v[110:111], v[6:7]
	v_pk_fma_f32 v[6:7], v[8:9], v[112:113], v[6:7]
	v_cvt_pk_f32_fp8_sdwa v[8:9], v10 src0_sel:WORD_1
	v_add_f32_e32 v4, v6, v7
	v_cvt_pk_f32_fp8_e32 v[6:7], v10
	v_cvt_pk_f32_fp8_sdwa v[10:11], v11 src0_sel:WORD_1
	v_pk_fma_f32 v[6:7], v[6:7], v[98:99], 0 op_sel_hi:[1,1,0]
	v_pk_fma_f32 v[6:7], v[8:9], v[100:101], v[6:7]
	v_cvt_pk_f32_fp8_sdwa v[8:9], v12 src0_sel:WORD_1
	v_pk_fma_f32 v[6:7], v[2:3], v[102:103], v[6:7]
	v_cvt_pk_f32_fp8_e32 v[2:3], v13
	v_pk_fma_f32 v[10:11], v[10:11], v[104:105], v[6:7]
	v_cvt_pk_f32_fp8_e32 v[6:7], v12
	v_cvt_pk_f32_fp8_sdwa v[12:13], v13 src0_sel:WORD_1
	v_pk_fma_f32 v[10:11], v[6:7], v[106:107], v[10:11]
	v_cvt_pk_f32_fp8_e32 v[6:7], v15
	v_pk_fma_f32 v[10:11], v[8:9], v[108:109], v[10:11]
	v_pk_fma_f32 v[10:11], v[2:3], v[110:111], v[10:11]
	v_pk_fma_f32 v[10:11], v[12:13], v[112:113], v[10:11]
	v_cvt_pk_f32_fp8_sdwa v[12:13], v14 src0_sel:WORD_1
	v_add_f32_e32 v8, v10, v11
	v_cvt_pk_f32_fp8_e32 v[10:11], v14
	v_cvt_pk_f32_fp8_sdwa v[14:15], v15 src0_sel:WORD_1
	v_pk_fma_f32 v[10:11], v[10:11], v[98:99], 0 op_sel_hi:[1,1,0]
	v_pk_fma_f32 v[10:11], v[12:13], v[100:101], v[10:11]
	v_cvt_pk_f32_fp8_sdwa v[12:13], v16 src0_sel:WORD_1
	v_pk_fma_f32 v[10:11], v[6:7], v[102:103], v[10:11]
	v_cvt_pk_f32_fp8_e32 v[6:7], v17
	v_pk_fma_f32 v[14:15], v[14:15], v[104:105], v[10:11]
	v_cvt_pk_f32_fp8_e32 v[10:11], v16
	v_cvt_pk_f32_fp8_sdwa v[16:17], v17 src0_sel:WORD_1
	s_waitcnt vmcnt(1)
; __device__ __forceinline__ f32x2 fp8x2_lo(unsigned w) { return __builtin_amdgcn_cvt_pk_f32_fp8(w, false); }
; __device__ __forceinline__ f32x2 fp8x2_hi(unsigned w) { return __builtin_amdgcn_cvt_pk_f32_fp8(w, true); }
; #define PA_IDS(T) do { const unsigned* kp_ = KP + (size_t)(T) * 256; _Pragma("unroll") for (int qq = 0; qq < 4; ++qq) idv[qq] = *(const u32x4*)(kp_ + 4 * qq); } while (0)
; template <bool NT>
; __device__ __forceinline__ void peer_passA(const Args& a, const PeerWork w) {
;     ...
;     int t = peer_tok(w, q), t1 = peer_tok(w, min(q + qs, ql));
;     PA_IDS(t);
;     PA_GATHER(t, ur, hv);
;     PA_IDS(t1);
; #pragma unroll 1
;     for (;; q += qs) {
;         u32x4 urn[16]; f32x4 hn[4];
;         PA_GATHER(t1, urn, hn);
;         const int t2 = peer_tok(w, min(q + 2 * qs, ql));
;         PA_IDS(t2);
;         float part[16];
; #pragma unroll
;         for (int k = 0; k < 16; ++k) {
;             const unsigned ww[4] = {ur[k].x, ur[k].y, ur[k].z, ur[k].w};
;             f32x2 p2 = {0.f, 0.f};
; #pragma unroll
;             for (int wd = 0; wd < 4; ++wd) { p2 = __builtin_elementwise_fma(fp8x2_lo(ww[wd]), (f32x2){hv[wd][0], hv[wd][1]}, p2); p2 = __builtin_elementwise_fma(fp8x2_hi(ww[wd]), (f32x2){hv[wd][2], hv[wd][3]}, p2); }
;             part[k] = p2[0] + p2[1];
	v_lshl_or_b32 v172, v30, 7, v1
	v_pk_fma_f32 v[14:15], v[10:11], v[106:107], v[14:15]
	v_cvt_pk_f32_fp8_e32 v[10:11], v23
	v_pk_fma_f32 v[14:15], v[12:13], v[108:109], v[14:15]
	v_lshl_or_b32 v173, v31, 7, v1
	v_pk_fma_f32 v[14:15], v[6:7], v[110:111], v[14:15]
	v_lshl_or_b32 v164, v32, 7, v1
	v_pk_fma_f32 v[14:15], v[16:17], v[112:113], v[14:15]
	v_cvt_pk_f32_fp8_sdwa v[16:17], v22 src0_sel:WORD_1
	v_add_f32_e32 v12, v14, v15
	v_cvt_pk_f32_fp8_e32 v[14:15], v22
	v_cvt_pk_f32_fp8_sdwa v[22:23], v23 src0_sel:WORD_1
	v_lshl_or_b32 v165, v33, 7, v1
	v_lshl_or_b32 v18, v18, 7, v1
	v_pk_fma_f32 v[14:15], v[14:15], v[98:99], 0 op_sel_hi:[1,1,0]
	v_lshl_or_b32 v19, v19, 7, v1
	v_pk_fma_f32 v[14:15], v[16:17], v[100:101], v[14:15]
	v_cvt_pk_f32_fp8_sdwa v[16:17], v24 src0_sel:WORD_1
	v_pk_fma_f32 v[14:15], v[10:11], v[102:103], v[14:15]
	v_cvt_pk_f32_fp8_e32 v[10:11], v25
	v_pk_fma_f32 v[22:23], v[22:23], v[104:105], v[14:15]
	v_cvt_pk_f32_fp8_e32 v[14:15], v24
	v_cvt_pk_f32_fp8_sdwa v[24:25], v25 src0_sel:WORD_1
	global_load_dwordx4 v[180:183], v172, s[10:11]
	global_load_dwordx4 v[176:179], v173, s[10:11]
	v_pk_fma_f32 v[22:23], v[14:15], v[106:107], v[22:23]
	v_cvt_pk_f32_fp8_e32 v[14:15], v27
	v_pk_fma_f32 v[22:23], v[16:17], v[108:109], v[22:23]
	global_load_dwordx4 v[172:175], v164, s[10:11]
	global_load_dwordx4 v[168:171], v165, s[10:11]
	v_pk_fma_f32 v[22:23], v[10:11], v[110:111], v[22:23]
	global_load_dwordx4 v[164:167], v18, s[10:11]
	global_load_dwordx4 v[160:163], v19, s[10:11]
	v_pk_fma_f32 v[22:23], v[24:25], v[112:113], v[22:23]
	v_cvt_pk_f32_fp8_sdwa v[24:25], v26 src0_sel:WORD_1
	v_add_f32_e32 v16, v22, v23
	v_cvt_pk_f32_fp8_e32 v[22:23], v26
	v_cvt_pk_f32_fp8_sdwa v[26:27], v27 src0_sel:WORD_1
	v_lshl_or_b32 v18, v20, 7, v1
	v_lshl_or_b32 v19, v21, 7, v1
	v_pk_fma_f32 v[22:23], v[22:23], v[98:99], 0 op_sel_hi:[1,1,0]
	global_load_dwordx4 v[150:153], v18, s[10:11]
	global_load_dwordx4 v[146:149], v19, s[10:11]
	v_pk_fma_f32 v[22:23], v[24:25], v[100:101], v[22:23]
	v_cvt_pk_f32_fp8_sdwa v[24:25], v28 src0_sel:WORD_1
	v_pk_fma_f32 v[22:23], v[14:15], v[102:103], v[22:23]
	v_cvt_pk_f32_fp8_e32 v[14:15], v29
	v_pk_fma_f32 v[26:27], v[26:27], v[104:105], v[22:23]
	v_cvt_pk_f32_fp8_e32 v[22:23], v28
	v_cvt_pk_f32_fp8_sdwa v[28:29], v29 src0_sel:WORD_1
	v_lshl_or_b32 v18, v62, 7, v1
	v_lshl_or_b32 v19, v63, 7, v1
	v_pk_fma_f32 v[26:27], v[22:23], v[106:107], v[26:27]
	v_cvt_pk_f32_fp8_e32 v[22:23], v35
	v_pk_fma_f32 v[26:27], v[24:25], v[108:109], v[26:27]
	global_load_dwordx4 v[142:145], v18, s[10:11]
	global_load_dwordx4 v[138:141], v19, s[10:11]
	v_pk_fma_f32 v[26:27], v[14:15], v[110:111], v[26:27]
	v_lshl_or_b32 v18, v64, 7, v1
	v_pk_fma_f32 v[26:27], v[28:29], v[112:113], v[26:27]
	v_cvt_pk_f32_fp8_sdwa v[28:29], v34 src0_sel:WORD_1
	v_add_f32_e32 v24, v26, v27
	v_cvt_pk_f32_fp8_e32 v[26:27], v34
	v_cvt_pk_f32_fp8_sdwa v[34:35], v35 src0_sel:WORD_1
	v_lshl_or_b32 v19, v65, 7, v1
	s_mov_b32 s18, s16
	v_pk_fma_f32 v[26:27], v[26:27], v[98:99], 0 op_sel_hi:[1,1,0]
	s_mov_b32 s16, s14
	v_pk_fma_f32 v[26:27], v[28:29], v[100:101], v[26:27]
	v_cvt_pk_f32_fp8_sdwa v[28:29], v36 src0_sel:WORD_1
	v_pk_fma_f32 v[26:27], v[22:23], v[102:103], v[26:27]
	v_cvt_pk_f32_fp8_e32 v[22:23], v37
	v_pk_fma_f32 v[34:35], v[34:35], v[104:105], v[26:27]
	v_cvt_pk_f32_fp8_e32 v[26:27], v36
	v_cvt_pk_f32_fp8_sdwa v[36:37], v37 src0_sel:WORD_1
	global_load_dwordx4 v[134:137], v18, s[10:11]
	global_load_dwordx4 v[130:133], v19, s[10:11]
	v_pk_fma_f32 v[34:35], v[26:27], v[106:107], v[34:35]
	v_cvt_pk_f32_fp8_e32 v[26:27], v39
	v_pk_fma_f32 v[34:35], v[28:29], v[108:109], v[34:35]
	v_lshl_or_b32 v18, v50, 7, v1
	v_pk_fma_f32 v[34:35], v[22:23], v[110:111], v[34:35]
	v_lshl_or_b32 v19, v51, 7, v1
	v_pk_fma_f32 v[34:35], v[36:37], v[112:113], v[34:35]
	v_cvt_pk_f32_fp8_sdwa v[36:37], v38 src0_sel:WORD_1
	v_add_f32_e32 v28, v34, v35
	v_cvt_pk_f32_fp8_e32 v[34:35], v38
	v_cvt_pk_f32_fp8_sdwa v[38:39], v39 src0_sel:WORD_1
	s_ashr_i32 s17, s14, 31
	v_pk_fma_f32 v[34:35], v[34:35], v[98:99], 0 op_sel_hi:[1,1,0]
	v_pk_fma_f32 v[34:35], v[36:37], v[100:101], v[34:35]
	v_cvt_pk_f32_fp8_sdwa v[36:37], v40 src0_sel:WORD_1
	v_pk_fma_f32 v[34:35], v[26:27], v[102:103], v[34:35]
	v_cvt_pk_f32_fp8_e32 v[26:27], v41
	v_pk_fma_f32 v[38:39], v[38:39], v[104:105], v[34:35]
	v_cvt_pk_f32_fp8_e32 v[34:35], v40
	v_cvt_pk_f32_fp8_sdwa v[40:41], v41 src0_sel:WORD_1
	global_load_dwordx4 v[126:129], v18, s[10:11]
	global_load_dwordx4 v[122:125], v19, s[10:11]
	v_pk_fma_f32 v[38:39], v[34:35], v[106:107], v[38:39]
	v_cvt_pk_f32_fp8_e32 v[34:35], v43
	v_pk_fma_f32 v[38:39], v[36:37], v[108:109], v[38:39]
	v_lshl_or_b32 v18, v52, 7, v1
	v_pk_fma_f32 v[38:39], v[26:27], v[110:111], v[38:39]
	v_lshl_or_b32 v19, v53, 7, v1
	v_pk_fma_f32 v[38:39], v[40:41], v[112:113], v[38:39]
	v_cvt_pk_f32_fp8_sdwa v[40:41], v42 src0_sel:WORD_1
	v_add_f32_e32 v36, v38, v39
	v_cvt_pk_f32_fp8_e32 v[38:39], v42
	v_cvt_pk_f32_fp8_sdwa v[42:43], v43 src0_sel:WORD_1
	s_lshl_b64 s[14:15], s[16:17], 12
	s_add_i32 s17, s12, s13
	v_pk_fma_f32 v[38:39], v[38:39], v[98:99], 0 op_sel_hi:[1,1,0]
	v_pk_fma_f32 v[38:39], v[40:41], v[100:101], v[38:39]
	v_cvt_pk_f32_fp8_sdwa v[40:41], v44 src0_sel:WORD_1
	v_pk_fma_f32 v[38:39], v[34:35], v[102:103], v[38:39]
	v_cvt_pk_f32_fp8_e32 v[34:35], v45
	v_pk_fma_f32 v[42:43], v[42:43], v[104:105], v[38:39]
	v_cvt_pk_f32_fp8_e32 v[38:39], v44
	v_cvt_pk_f32_fp8_sdwa v[44:45], v45 src0_sel:WORD_1
	global_load_dwordx4 v[118:121], v18, s[10:11]
	global_load_dwordx4 v[114:117], v19, s[10:11]
	v_pk_fma_f32 v[42:43], v[38:39], v[106:107], v[42:43]
	v_cvt_pk_f32_fp8_e32 v[38:39], v47
; __device__ __forceinline__ f32x2 fp8x2_lo(unsigned w) { return __builtin_amdgcn_cvt_pk_f32_fp8(w, false); }
; __device__ __forceinline__ f32x2 fp8x2_hi(unsigned w) { return __builtin_amdgcn_cvt_pk_f32_fp8(w, true); }
; #define PA_IDS(T) do { const unsigned* kp_ = KP + (size_t)(T) * 256; _Pragma("unroll") for (int qq = 0; qq < 4; ++qq) idv[qq] = *(const u32x4*)(kp_ + 4 * qq); } while (0)
; template <bool NT>
; __device__ __forceinline__ void peer_passA(const Args& a, const PeerWork w) {
;     ...
;     int t = peer_tok(w, q), t1 = peer_tok(w, min(q + qs, ql));
;     PA_IDS(t);
;     PA_GATHER(t, ur, hv);
;     PA_IDS(t1);
; #pragma unroll 1
;     for (;; q += qs) {
;         u32x4 urn[16]; f32x4 hn[4];
;         PA_GATHER(t1, urn, hn);
;         const int t2 = peer_tok(w, min(q + 2 * qs, ql));
;         PA_IDS(t2);
;         float part[16];
; #pragma unroll
;         for (int k = 0; k < 16; ++k) {
;             const unsigned ww[4] = {ur[k].x, ur[k].y, ur[k].z, ur[k].w};
;             f32x2 p2 = {0.f, 0.f};
; #pragma unroll
;             for (int wd = 0; wd < 4; ++wd) { p2 = __builtin_elementwise_fma(fp8x2_lo(ww[wd]), (f32x2){hv[wd][0], hv[wd][1]}, p2); p2 = __builtin_elementwise_fma(fp8x2_hi(ww[wd]), (f32x2){hv[wd][2], hv[wd][3]}, p2); }
;             part[k] = p2[0] + p2[1];
	v_pk_fma_f32 v[42:43], v[40:41], v[108:109], v[42:43]
	v_lshl_add_u64 v[18:19], v[156:157], 0, s[14:15]
	v_pk_fma_f32 v[42:43], v[34:35], v[110:111], v[42:43]
	s_min_i32 s14, s17, 0x3fff
	v_pk_fma_f32 v[42:43], v[44:45], v[112:113], v[42:43]
	v_cvt_pk_f32_fp8_sdwa v[44:45], v46 src0_sel:WORD_1
	v_add_f32_e32 v40, v42, v43
	v_cvt_pk_f32_fp8_e32 v[42:43], v46
	v_cvt_pk_f32_fp8_sdwa v[46:47], v47 src0_sel:WORD_1
	s_ashr_i32 s15, s14, 31
	s_lshl_b64 s[28:29], s[14:15], 10
	v_pk_fma_f32 v[42:43], v[42:43], v[98:99], 0 op_sel_hi:[1,1,0]
	v_lshl_add_u64 v[30:31], v[154:155], 0, s[28:29]
	v_pk_fma_f32 v[42:43], v[44:45], v[100:101], v[42:43]
	v_cvt_pk_f32_fp8_sdwa v[44:45], v48 src0_sel:WORD_1
	v_pk_fma_f32 v[42:43], v[38:39], v[102:103], v[42:43]
	v_cvt_pk_f32_fp8_e32 v[38:39], v49
	v_pk_fma_f32 v[46:47], v[46:47], v[104:105], v[42:43]
	v_cvt_pk_f32_fp8_e32 v[42:43], v48
	v_cvt_pk_f32_fp8_sdwa v[48:49], v49 src0_sel:WORD_1
	global_load_dwordx4 v[82:85], v[18:19], off offset:48
	global_load_dwordx4 v[86:89], v[18:19], off offset:32
	global_load_dwordx4 v[90:93], v[18:19], off offset:16
	global_load_dwordx4 v[94:97], v[18:19], off
	global_load_dwordx4 v[50:53], v[30:31], off offset:48
	global_load_dwordx4 v[62:65], v[30:31], off offset:32
	s_nop 0
	global_load_dwordx4 v[18:21], v[30:31], off offset:16
	s_nop 0
	global_load_dwordx4 v[30:33], v[30:31], off
	v_pk_fma_f32 v[46:47], v[42:43], v[106:107], v[46:47]
	v_cvt_pk_f32_fp8_e32 v[42:43], v55
	v_pk_fma_f32 v[46:47], v[44:45], v[108:109], v[46:47]
	s_ashr_i32 s19, s18, 31
	v_pk_fma_f32 v[46:47], v[38:39], v[110:111], v[46:47]
	s_lshl_b64 s[18:19], s[18:19], 11
	v_pk_fma_f32 v[46:47], v[48:49], v[112:113], v[46:47]
	v_cvt_pk_f32_fp8_sdwa v[48:49], v54 src0_sel:WORD_1
	v_add_f32_e32 v44, v46, v47
	v_cvt_pk_f32_fp8_e32 v[46:47], v54
	v_cvt_pk_f32_fp8_sdwa v[54:55], v55 src0_sel:WORD_1
	s_add_i32 s12, s22, s12
	s_cmpk_gt_i32 s12, 0x3fff
	v_pk_fma_f32 v[46:47], v[46:47], v[98:99], 0 op_sel_hi:[1,1,0]
	v_readfirstlane_b32 s12, v0
	v_pk_fma_f32 v[46:47], v[48:49], v[100:101], v[46:47]
	v_cvt_pk_f32_fp8_sdwa v[48:49], v56 src0_sel:WORD_1
	v_pk_fma_f32 v[46:47], v[42:43], v[102:103], v[46:47]
	v_cvt_pk_f32_fp8_e32 v[42:43], v57
	v_pk_fma_f32 v[54:55], v[54:55], v[104:105], v[46:47]
	v_cvt_pk_f32_fp8_e32 v[46:47], v56
	v_cvt_pk_f32_fp8_sdwa v[56:57], v57 src0_sel:WORD_1
	v_pk_fma_f32 v[54:55], v[46:47], v[106:107], v[54:55]
	s_nop 0
	v_pk_fma_f32 v[54:55], v[48:49], v[108:109], v[54:55]
	v_cvt_pk_f32_fp8_e32 v[46:47], v59
	v_pk_fma_f32 v[54:55], v[42:43], v[110:111], v[54:55]
	s_nop 0
	v_pk_fma_f32 v[54:55], v[56:57], v[112:113], v[54:55]
	v_cvt_pk_f32_fp8_sdwa v[56:57], v58 src0_sel:WORD_1
	v_add_f32_e32 v48, v54, v55
	v_cvt_pk_f32_fp8_e32 v[54:55], v58
	v_cvt_pk_f32_fp8_sdwa v[58:59], v59 src0_sel:WORD_1
	v_pk_fma_f32 v[54:55], v[54:55], v[98:99], 0 op_sel_hi:[1,1,0]
	s_nop 0
	v_pk_fma_f32 v[54:55], v[56:57], v[100:101], v[54:55]
	v_cvt_pk_f32_fp8_sdwa v[56:57], v60 src0_sel:WORD_1
	v_pk_fma_f32 v[54:55], v[46:47], v[102:103], v[54:55]
	v_cvt_pk_f32_fp8_e32 v[46:47], v61
	v_pk_fma_f32 v[58:59], v[58:59], v[104:105], v[54:55]
	v_cvt_pk_f32_fp8_e32 v[54:55], v60
	v_cvt_pk_f32_fp8_sdwa v[60:61], v61 src0_sel:WORD_1
	v_pk_fma_f32 v[58:59], v[54:55], v[106:107], v[58:59]
	s_nop 0
	v_pk_fma_f32 v[58:59], v[56:57], v[108:109], v[58:59]
	v_cvt_pk_f32_fp8_e32 v[54:55], v67
	v_pk_fma_f32 v[58:59], v[46:47], v[110:111], v[58:59]
	s_nop 0
	v_pk_fma_f32 v[58:59], v[60:61], v[112:113], v[58:59]
	v_cvt_pk_f32_fp8_sdwa v[60:61], v66 src0_sel:WORD_1
	v_add_f32_e32 v56, v58, v59
	v_cvt_pk_f32_fp8_e32 v[58:59], v66
	v_cvt_pk_f32_fp8_sdwa v[66:67], v67 src0_sel:WORD_1
	v_pk_fma_f32 v[58:59], v[58:59], v[98:99], 0 op_sel_hi:[1,1,0]
	s_nop 0
	v_pk_fma_f32 v[58:59], v[60:61], v[100:101], v[58:59]
	v_cvt_pk_f32_fp8_sdwa v[60:61], v68 src0_sel:WORD_1
	v_pk_fma_f32 v[58:59], v[54:55], v[102:103], v[58:59]
	v_cvt_pk_f32_fp8_e32 v[54:55], v69
	v_pk_fma_f32 v[66:67], v[66:67], v[104:105], v[58:59]
	v_cvt_pk_f32_fp8_e32 v[58:59], v68
	v_cvt_pk_f32_fp8_sdwa v[68:69], v69 src0_sel:WORD_1
	v_pk_fma_f32 v[66:67], v[58:59], v[106:107], v[66:67]
	s_nop 0
	v_pk_fma_f32 v[66:67], v[60:61], v[108:109], v[66:67]
	v_cvt_pk_f32_fp8_e32 v[58:59], v71
	v_pk_fma_f32 v[66:67], v[54:55], v[110:111], v[66:67]
	s_nop 0
	v_pk_fma_f32 v[66:67], v[68:69], v[112:113], v[66:67]
	v_cvt_pk_f32_fp8_sdwa v[68:69], v70 src0_sel:WORD_1
	v_add_f32_e32 v60, v66, v67
	v_cvt_pk_f32_fp8_e32 v[66:67], v70
	v_cvt_pk_f32_fp8_sdwa v[70:71], v71 src0_sel:WORD_1
	v_pk_fma_f32 v[66:67], v[66:67], v[98:99], 0 op_sel_hi:[1,1,0]
	s_nop 0
	v_pk_fma_f32 v[66:67], v[68:69], v[100:101], v[66:67]
	v_cvt_pk_f32_fp8_sdwa v[68:69], v72 src0_sel:WORD_1
	v_pk_fma_f32 v[66:67], v[58:59], v[102:103], v[66:67]
	v_cvt_pk_f32_fp8_e32 v[58:59], v73
	v_pk_fma_f32 v[70:71], v[70:71], v[104:105], v[66:67]
	v_cvt_pk_f32_fp8_e32 v[66:67], v72
	v_cvt_pk_f32_fp8_sdwa v[72:73], v73 src0_sel:WORD_1
; __device__ __forceinline__ unsigned cvt_pk_bf16(float lo, float hi) { unsigned r; asm volatile("v_cvt_pk_bf16_f32 %0, %1, %2" : "=v"(r) : "v"(lo), "v"(hi)); return r; }
; template <int CTRL> __device__ __forceinline__ float dpp_f(float x) { return __uint_as_float((unsigned)__builtin_amdgcn_update_dpp(0, (int)__float_as_uint(x), CTRL, 0xf, 0xf, false)); }
; __device__ __forceinline__ f32x2 fp8x2_lo(unsigned w) { return __builtin_amdgcn_cvt_pk_f32_fp8(w, false); }
; __device__ __forceinline__ f32x2 fp8x2_hi(unsigned w) { return __builtin_amdgcn_cvt_pk_f32_fp8(w, true); }
; __device__ __forceinline__ float xor4_f(float x) { float r = dpp_bank_f<0x104, 0x5>(0.f, x); return dpp_bank_f<0x114, 0xa>(r, x); }
; template <bool NT>
; __device__ __forceinline__ void peer_passA(const Args& a, const PeerWork w) {
;     ...
;         for (int k = 0; k < 16; ++k) {
;             const unsigned ww[4] = {ur[k].x, ur[k].y, ur[k].z, ur[k].w};
;             f32x2 p2 = {0.f, 0.f};
; #pragma unroll
;             for (int wd = 0; wd < 4; ++wd) { p2 = __builtin_elementwise_fma(fp8x2_lo(ww[wd]), (f32x2){hv[wd][0], hv[wd][1]}, p2); p2 = __builtin_elementwise_fma(fp8x2_hi(ww[wd]), (f32x2){hv[wd][2], hv[wd][3]}, p2); }
;             part[k] = p2[0] + p2[1];
;         }
;         float w8[8], w4[4], w2[2];
;         { const bool up = (lane & 4) != 0;
; #pragma unroll
;           for (int m = 0; m < 8; ++m) { const float keep = up ? part[m + 8] : part[m], send = up ? part[m] : part[m + 8]; w8[m] = keep + xor4_f(send); } }
;         { const bool up = (lane & 2) != 0;
; #pragma unroll
;           for (int m = 0; m < 4; ++m) { const float keep = up ? w8[m + 4] : w8[m], send = up ? w8[m] : w8[m + 4]; w4[m] = keep + dpp_f<0x4E>(send); } }
;         { const bool up = (lane & 1) != 0;
; #pragma unroll
;           for (int m = 0; m < 2; ++m) { const float keep = up ? w4[m + 2] : w4[m], send = up ? w4[m] : w4[m + 2]; w2[m] = keep + dpp_f<0xB1>(send); } }
;         PD[(size_t)t * 512] = cvt_pk_bf16(w2[0], w2[1]);
;         if (q + qs > ql) break;
; #pragma unroll
;         for (int k = 0; k < 16; ++k) ur[k] = urn[k];
; #pragma unroll
;         for (int qq = 0; qq < 4; ++qq) hv[qq] = hn[qq];
;         t = t1; t1 = t2;
;     }
	v_pk_fma_f32 v[70:71], v[66:67], v[106:107], v[70:71]
	s_nop 0
	v_pk_fma_f32 v[70:71], v[68:69], v[108:109], v[70:71]
	v_cvt_pk_f32_fp8_e32 v[66:67], v75
	v_pk_fma_f32 v[70:71], v[58:59], v[110:111], v[70:71]
	s_nop 0
	v_pk_fma_f32 v[70:71], v[72:73], v[112:113], v[70:71]
	v_cvt_pk_f32_fp8_sdwa v[72:73], v74 src0_sel:WORD_1
	v_add_f32_e32 v68, v70, v71
	v_cvt_pk_f32_fp8_e32 v[70:71], v74
	v_cvt_pk_f32_fp8_sdwa v[74:75], v75 src0_sel:WORD_1
	v_pk_fma_f32 v[70:71], v[70:71], v[98:99], 0 op_sel_hi:[1,1,0]
	s_nop 0
	v_pk_fma_f32 v[70:71], v[72:73], v[100:101], v[70:71]
	v_cvt_pk_f32_fp8_sdwa v[72:73], v76 src0_sel:WORD_1
	v_pk_fma_f32 v[70:71], v[66:67], v[102:103], v[70:71]
	v_cvt_pk_f32_fp8_e32 v[66:67], v77
	v_pk_fma_f32 v[74:75], v[74:75], v[104:105], v[70:71]
	v_cvt_pk_f32_fp8_e32 v[70:71], v76
	v_cvt_pk_f32_fp8_sdwa v[76:77], v77 src0_sel:WORD_1
	v_pk_fma_f32 v[74:75], v[70:71], v[106:107], v[74:75]
	s_nop 0
	v_pk_fma_f32 v[74:75], v[72:73], v[108:109], v[74:75]
	v_cvt_pk_f32_fp8_e32 v[70:71], v79
	v_pk_fma_f32 v[74:75], v[66:67], v[110:111], v[74:75]
	s_nop 0
	v_pk_fma_f32 v[74:75], v[76:77], v[112:113], v[74:75]
	v_cvt_pk_f32_fp8_sdwa v[76:77], v78 src0_sel:WORD_1
	v_add_f32_e32 v72, v74, v75
	v_cvt_pk_f32_fp8_e32 v[74:75], v78
	v_cvt_pk_f32_fp8_sdwa v[78:79], v79 src0_sel:WORD_1
	v_pk_fma_f32 v[98:99], v[74:75], v[98:99], 0 op_sel_hi:[1,1,0]
	s_nop 0
	v_pk_fma_f32 v[98:99], v[76:77], v[100:101], v[98:99]
	v_cvt_pk_f32_fp8_e32 v[100:101], v81
	v_pk_fma_f32 v[102:103], v[70:71], v[102:103], v[98:99]
	v_cvt_pk_f32_fp8_sdwa v[98:99], v80 src0_sel:WORD_1
	v_pk_fma_f32 v[102:103], v[78:79], v[104:105], v[102:103]
	v_cvt_pk_f32_fp8_e32 v[104:105], v80
	v_cvt_pk_f32_fp8_sdwa v[78:79], v81 src0_sel:WORD_1
	v_pk_fma_f32 v[106:107], v[104:105], v[106:107], v[102:103]
	s_nop 0
	v_pk_fma_f32 v[106:107], v[98:99], v[108:109], v[106:107]
	v_pk_fma_f32 v[110:111], v[100:101], v[110:111], v[106:107]
	v_pk_fma_f32 v[110:111], v[78:79], v[112:113], v[110:111]
	v_cndmask_b32_e64 v112, v186, v40, s[0:1]
	v_add_f32_e32 v110, v110, v111
	v_cndmask_b32_e64 v111, v40, v186, s[0:1]
	s_nop 0
	v_add_f32_dpp v111, v112, v111 row_half_mirror row_mask:0xf bank_mask:0xf bound_ctrl:1
	v_cndmask_b32_e64 v113, v4, v44, s[0:1]
	v_cndmask_b32_e64 v112, v44, v4, s[0:1]
	s_nop 0
	v_add_f32_dpp v112, v113, v112 row_half_mirror row_mask:0xf bank_mask:0xf bound_ctrl:1
	v_cndmask_b32_e64 v106, v8, v48, s[0:1]
	v_cndmask_b32_e64 v113, v48, v8, s[0:1]
	s_nop 0
	s_nop 0
	v_add_f32_dpp v113, v106, v113 row_half_mirror row_mask:0xf bank_mask:0xf bound_ctrl:1
	v_cndmask_b32_e64 v107, v12, v56, s[0:1]
	v_cndmask_b32_e64 v106, v56, v12, s[0:1]
	s_nop 0
	s_nop 0
	v_add_f32_dpp v106, v107, v106 row_half_mirror row_mask:0xf bank_mask:0xf bound_ctrl:1
	v_cndmask_b32_e64 v108, v16, v60, s[0:1]
	v_cndmask_b32_e64 v107, v60, v16, s[0:1]
	s_nop 0
	s_nop 0
	v_add_f32_dpp v107, v108, v107 row_half_mirror row_mask:0xf bank_mask:0xf bound_ctrl:1
	v_cndmask_b32_e64 v109, v24, v68, s[0:1]
	v_cndmask_b32_e64 v108, v68, v24, s[0:1]
	s_nop 0
	s_nop 0
	v_add_f32_dpp v108, v109, v108 row_half_mirror row_mask:0xf bank_mask:0xf bound_ctrl:1
	v_cndmask_b32_e64 v102, v28, v72, s[0:1]
	v_cndmask_b32_e64 v109, v72, v28, s[0:1]
	s_nop 0
	s_nop 0
	v_add_f32_dpp v109, v102, v109 row_half_mirror row_mask:0xf bank_mask:0xf bound_ctrl:1
	v_cndmask_b32_e64 v102, v110, v36, s[0:1]
	v_cndmask_b32_e64 v110, v36, v110, s[0:1]
	v_mov_b32_e32 v103, 0
	s_nop 1
	s_nop 0
	v_add_f32_dpp v110, v110, v102 row_half_mirror row_mask:0xf bank_mask:0xf bound_ctrl:1
	v_cndmask_b32_e64 v102, v107, v111, s[4:5]
	v_cndmask_b32_e64 v111, v111, v107, s[4:5]
	v_cndmask_b32_e64 v107, v108, v112, s[4:5]
	v_cndmask_b32_e64 v112, v112, v108, s[4:5]
	v_add_f32_dpp v111, v111, v102 quad_perm:[2,3,0,1] row_mask:0xf bank_mask:0xf bound_ctrl:1
	s_nop 0
	v_add_f32_dpp v112, v112, v107 quad_perm:[2,3,0,1] row_mask:0xf bank_mask:0xf bound_ctrl:1
	v_cndmask_b32_e64 v107, v109, v113, s[4:5]
	v_cndmask_b32_e64 v113, v113, v109, s[4:5]
	s_nop 1
	v_add_f32_dpp v113, v113, v107 quad_perm:[2,3,0,1] row_mask:0xf bank_mask:0xf bound_ctrl:1
	v_cndmask_b32_e64 v107, v110, v106, s[4:5]
	v_cndmask_b32_e64 v110, v106, v110, s[4:5]
	v_cndmask_b32_e64 v106, v113, v111, s[6:7]
	v_cndmask_b32_e64 v111, v111, v113, s[6:7]
	v_add_f32_dpp v110, v110, v107 quad_perm:[2,3,0,1] row_mask:0xf bank_mask:0xf bound_ctrl:1
	v_cndmask_b32_e64 v113, v110, v112, s[6:7]
	v_cndmask_b32_e64 v110, v112, v110, s[6:7]
	v_add_f32_dpp v111, v111, v106 quad_perm:[1,0,3,2] row_mask:0xf bank_mask:0xf bound_ctrl:1
	s_nop 0
	v_add_f32_dpp v110, v110, v113 quad_perm:[1,0,3,2] row_mask:0xf bank_mask:0xf bound_ctrl:1
	v_cvt_pk_bf16_f32 v112, v111, v110
	v_lshl_add_u64 v[110:111], v[158:159], 0, s[18:19]
	s_mov_b64 s[18:19], -1
	global_store_dword v[110:111], v112, off
	s_cbranch_scc1 .Lpa_x2_a6
	s_sub_i32 s12, s17, s22
	s_mov_b64 s[18:19], 0
	s_branch .LBB0_1321
